# SSD chunk loop: x-branch conv weights staged once per item in spare LDS instead of 10 global loads per chunk
# baseline (speedup 1.0000x reference)
; __device__ __forceinline__ int lane_fresh() { int l; asm volatile("v_mbcnt_lo_u32_b32 %0, -1, 0\n\tv_mbcnt_hi_u32_b32 %0, -1, %0" : "=v"(l)); return l; }
; __device__ __forceinline__ void ssd_prompt_item(const Params& p, int item, const int wv) {
;   const int lane = lane_fresh(), wid = wv, tid = wv * 64 + lane, fr = lane & 15, fq = lane >> 4;
;   const int h = item & 15, b = item >> 4, g = h >> 3;
;   char* ws = p.ws;
;   u16* C_l = (u16*)g_shm;
;   u16* B_l = C_l + 128 * 136;
;   u16* G_l = B_l;
;   u16* BT_l = B_l + 128 * 136;
;   u16* xT_l = BT_l + 128 * 136;
;   u16* xw_l = xT_l + 64 * 136;
;   u16* h_l = xw_l + 64 * 136;
;   float* acum_l = (float*)(h_l + 64 * 136);
;   float* dt_l = acum_l + 128;
;   const u16* XBC = (const u16*)(ws + OFF_XBC);
;   const u16* ZS = (const u16*)(ws + OFF_ZS);
;   const float* DT = (const float*)(ws + OFF_DT);
;   u16* Y = (u16*)((char*)p.out + OOFF_XN);
;   float* YPS = (float*)(ws + OFF_YPS);
;   const float Ah = -__expf(p.in[16][h]);
;   const float Dh = p.in[17][h];
;   const float* convw = p.in[13];
;   const float* convb = p.in[14];
;   const int cc = tid & 31, rg = tid >> 5;
;   const int colbc = (cc < 16) ? (1024 + g * 128 + cc * 8) : (1280 + g * 128 + (cc - 16) * 8);
;   const int xc = tid & 7, xr = tid >> 3;
;   const int colx = h * 64 + xc * 8;
;   const int j0 = rg * 8;
;   f32x4 hacc[4];
; #pragma unroll
;   for (int pb = 0; pb < 4; ++pb) hacc[pb] = (f32x4){0.f, 0.f, 0.f, 0.f};
;   u32x4 u[11], ux[5];
;   float a0 = 0.f, a1 = 0.f;
.LBB0_568:
	v_writelane_b32 v250, s68, 22
	s_and_b32 s19, s68, 0x7f
	v_writelane_b32 v250, s19, 23
	v_writelane_b32 v250, s45, 24
	v_writelane_b32 v250, s44, 25
	s_lshl_b32 s19, s45, 7
	v_writelane_b32 v250, s40, 26
	v_ashrrev_i32_e32 v77, 4, v71
	s_and_b32 s87, s19, 0x3800
	s_and_b32 s19, s44, 15
	s_waitcnt vmcnt(0)
	v_mul_f32_e32 v69, 0x3fb8aa3b, v69
	v_lshlrev_b32_e32 v194, 3, v77
	v_readlane_b32 s4, v250, 5
	s_lshl_b32 s86, s44, 3
	s_and_b32 s85, s40, 7
	s_lshl_b32 s84, s19, 7
	v_exp_f32_e32 v193, v69
	v_cndmask_b32_e64 v56, 0, v56, s[6:7]
	v_cndmask_b32_e64 v57, 0, v57, s[6:7]
	v_cndmask_b32_e64 v58, 0, v58, s[6:7]
	v_cndmask_b32_e64 v59, 0, v59, s[6:7]
	v_cndmask_b32_e64 v60, 0, v60, s[6:7]
	v_cndmask_b32_e64 v61, 0, v61, s[6:7]
	v_cndmask_b32_e64 v62, 0, v62, s[6:7]
	v_cndmask_b32_e64 v63, 0, v63, s[6:7]
	v_add_u32_e32 v69, s4, v194
	v_readlane_b32 s4, v250, 10
	v_cmp_gt_i32_e64 s[6:7], 1, v71
	v_cndmask_b32_e64 v44, 0, v44, s[10:11]
	v_cndmask_b32_e64 v45, 0, v45, s[10:11]
	v_cndmask_b32_e64 v46, 0, v46, s[10:11]
	v_cndmask_b32_e64 v47, 0, v47, s[10:11]
	v_cndmask_b32_e64 v48, 0, v48, s[8:9]
	v_cndmask_b32_e64 v49, 0, v49, s[8:9]
	v_cndmask_b32_e64 v50, 0, v50, s[8:9]
	v_cndmask_b32_e64 v51, 0, v51, s[8:9]
	v_cndmask_b32_e64 v52, 0, v52, s[8:9]
	v_cndmask_b32_e64 v53, 0, v53, s[8:9]
	v_cndmask_b32_e64 v54, 0, v54, s[8:9]
	v_cndmask_b32_e64 v55, 0, v55, s[8:9]
	v_readlane_b32 s8, v250, 14
	v_readlane_b32 s5, v250, 11
	s_add_u32 s12, s4, s18
	v_readlane_b32 s90, v250, 19
	v_readlane_b32 s11, v250, 16
	v_readlane_b32 s18, v250, 17
	v_readlane_b32 s19, v250, 18
	v_readlane_b32 s10, v250, 15
	v_writelane_b32 v250, s6, 27
	v_lshlrev_b32_e32 v87, 2, v71
	s_movk_i32 s9, 0x110
	v_writelane_b32 v250, s7, 28
	v_cmp_gt_i32_e64 s[6:7], 2, v71
	v_lshlrev_b32_e32 v142, 2, v75
	s_addc_u32 s13, s5, 0
	v_writelane_b32 v250, s6, 29
	v_and_b32_e32 v196, -16, v71
	v_lshrrev_b32_e32 v79, 4, v64
	v_writelane_b32 v250, s7, 30
	v_cmp_gt_i32_e64 s[6:7], 4, v71
	v_and_b32_e32 v80, 0x78, v65
	s_add_i32 s4, 16, 0x22000
	v_writelane_b32 v250, s6, 31
	v_lshl_add_u32 v160, v72, 4, 16
	v_mul_lo_u32 v208, v66, s9
	v_writelane_b32 v250, s7, 32
	v_cmp_gt_i32_e64 s[6:7], 8, v71
	v_and_b32_e32 v192, 15, v71
	v_lshl_add_u64 v[150:151], s[22:23], 0, v[142:143]
	v_writelane_b32 v250, s6, 33
	v_lshl_add_u64 v[152:153], s[24:25], 0, v[142:143]
	v_lshlrev_b32_e32 v142, 2, v76
	v_writelane_b32 v250, s7, 34
	v_cmp_gt_i32_e64 s[6:7], 16, v71
	v_lshlrev_b32_e32 v158, 2, v77
	v_lshlrev_b32_e32 v81, 1, v80
	v_writelane_b32 v250, s6, 35
	v_add_u32_e32 v82, s4, v196
	v_and_b32_e32 v64, 16, v71
	v_writelane_b32 v250, s7, 36
	s_movk_i32 s6, 0x80
	v_bitop3_b32 v207, v87, s6, v161 bitop3:0x6c
	v_cmp_gt_i32_e64 s[6:7], 32, v71
	v_cmp_gt_u32_e64 s[4:5], 16, v71
	v_mul_u32_u24_e32 v71, 0x880, v72
	v_writelane_b32 v250, s6, 37
	v_lshlrev_b32_e32 v72, 1, v66
	v_lshl_add_u64 v[154:155], s[24:25], 0, v[142:143]
	v_lshrrev_b32_e32 v43, 5, v142
	v_and_b32_e32 v43, 7, v43
	v_mul_u32_u24_e32 v43, 0xa0, v43
	v_add_u32_e32 v43, 0x26810, v43
	v_writelane_b32 v250, s7, 38
	s_movk_i32 s6, 0xff00
	v_add3_u32 v209, v160, v208, s6
	v_mad_u64_u32 v[168:169], s[6:7], v74, s9, v[160:161]
	v_mul_lo_u32 v74, v79, s9
	v_lshl_add_u64 v[156:157], s[22:23], 0, v[142:143]
	v_or_b32_e32 v75, s90, v192
	s_mov_b64 s[24:25], 0x4800
	v_add3_u32 v210, s19, v71, v72
	v_lshlrev_b32_e32 v72, 2, v80
	v_add3_u32 v212, s8, v81, v74
	v_add3_u32 v216, s10, v81, v74
	v_or_b32_e32 v74, 2, v158
	s_movk_i32 s6, 0x440
	v_add_u32_e32 v80, 19, v158
	v_lshl_add_u64 v[166:167], v[150:151], 0, s[24:25]
	v_lshl_add_u64 v[174:175], v[156:157], 0, s[24:25]
	v_cmp_gt_i32_e64 s[24:25], v74, v75
	v_mul_lo_u32 v74, v77, s6
	v_cmp_gt_i32_e64 s[6:7], v80, v75
	v_add_u32_e32 v79, 18, v158
	v_add_u32_e32 v211, s18, v72
	v_writelane_b32 v250, s6, 39
	v_add_u32_e32 v213, s11, v72
	v_or_b32_e32 v72, 16, v72
	v_writelane_b32 v250, s7, 40
	v_cmp_gt_i32_e64 s[6:7], v79, v75
	v_add_u32_e32 v77, 17, v158
	s_mov_b64 s[22:23], 0x3000
	v_writelane_b32 v250, s6, 41
	v_add_u32_e32 v214, s18, v72
	v_add_u32_e32 v215, s11, v72
	v_or_b32_e32 v72, 3, v158
	v_writelane_b32 v250, s7, 42
	v_cmp_gt_i32_e64 s[6:7], v77, v75
	v_lshl_add_u64 v[164:165], v[150:151], 0, s[22:23]
	v_lshl_add_u64 v[172:173], v[156:157], 0, s[22:23]
	v_cmp_gt_i32_e64 s[22:23], v72, v75
	v_add_u32_e32 v72, 16, v158
	v_writelane_b32 v250, s6, 43
	v_lshlrev_b32_e32 v85, 2, v73
	v_lshl_add_u32 v197, v75, 2, s11
	v_writelane_b32 v250, s7, 44
	v_cmp_gt_i32_e64 s[6:7], v72, v75
	v_add_u32_e32 v72, 32, v158
	v_cmp_gt_i32_e64 s[42:43], v72, v75
	v_add_u32_e32 v72, 48, v158
	v_add_u32_e32 v198, s11, v196
	v_add_u32_e32 v200, s18, v85
	v_add_u32_e32 v201, s11, v85
	v_add_u32_e32 v85, s10, v196
	v_cmp_gt_i32_e64 s[10:11], v72, v75
	v_add_u32_e32 v72, 64, v158
	v_cmp_gt_i32_e64 s[58:59], v72, v75
	v_add_u32_e32 v72, 0x50, v158
	v_cmp_gt_i32_e64 s[66:67], v72, v75
	v_add_u32_e32 v72, 0x60, v158
	v_cmp_gt_i32_e64 s[74:75], v72, v75
	v_add_u32_e32 v72, 0x70, v158
	v_add_u32_e32 v68, s87, v68
	v_lshl_or_b32 v142, v67, 1, s84
	v_cmp_gt_i32_e64 s[82:83], v72, v75
	v_add_u32_e32 v217, s87, v73
	v_mad_i64_i32 v[72:73], s[88:89], v68, s33, v[142:143]
; __device__ __forceinline__ void ssd_prompt_item(const Params& p, int item, const int wv) {
;     ...
;   const int cc = tid & 31, rg = tid >> 5;
;   const int colbc = (cc < 16) ? (1024 + g * 128 + cc * 8) : (1280 + g * 128 + (cc - 16) * 8);
;   const int xc = tid & 7, xr = tid >> 3;
;   const int colx = h * 64 + xc * 8;
;   const int j0 = rg * 8;
;   f32x4 hacc[4];
; #pragma unroll
;   for (int pb = 0; pb < 4; ++pb) hacc[pb] = (f32x4){0.f, 0.f, 0.f, 0.f};
;   u32x4 u[11], ux[5];
;   float a0 = 0.f, a1 = 0.f;
;     ...
;       f32x4 b0 = *(const f32x4*)(convb + colx), b1 = *(const f32x4*)(convb + colx + 4);
;       f32x4 w0[4], w1[4];
; #pragma unroll
;       for (int k = 0; k < 4; ++k) { w0[k] = *(const f32x4*)(convw + k * 1536 + colx); w1[k] = *(const f32x4*)(convw + k * 1536 + colx + 4); }
	v_mul_u32_u24_e32 v71, 0x110, v67
	s_mov_b64 s[88:89], 0x730e000
	v_add_u32_e32 v67, 0x80, v68
	v_writelane_b32 v250, s6, 45
	v_add_u32_e32 v80, 35, v158
	v_lshl_add_u64 v[176:177], v[72:73], 0, s[88:89]
	v_mad_i64_i32 v[72:73], s[88:89], v67, s33, v[142:143]
	v_add_u32_e32 v67, 0x7e, v68
	v_writelane_b32 v250, s7, 46
	v_cmp_gt_i32_e64 s[6:7], v80, v75
	s_mov_b64 s[92:93], 0x72aec00
	v_mad_i64_i32 v[180:181], s[88:89], v67, s33, v[142:143]
	v_add_u32_e32 v67, 0x7c, v68
	s_add_i32 s41, s90, s41
	v_add_u32_e32 v79, 34, v158
	v_writelane_b32 v250, s6, 47
	v_lshl_add_u64 v[178:179], v[72:73], 0, s[92:93]
	v_mad_i64_i32 v[72:73], s[88:89], v67, s33, v[142:143]
	v_add_u32_e32 v142, s41, v192
	v_writelane_b32 v250, s7, 48
	v_cmp_gt_i32_e64 s[6:7], v79, v75
	v_lshlrev_b64 v[184:185], 7, v[142:143]
	v_add_u32_e32 v77, 33, v158
	v_writelane_b32 v250, s6, 49
	v_add_u32_e32 v218, s87, v66
	v_and_or_b32 v66, s86, 64, v184
	v_writelane_b32 v250, s7, 50
	v_cmp_gt_i32_e64 s[6:7], v77, v75
	v_lshl_or_b32 v184, s85, 3, v66
	v_lshlrev_b64 v[66:67], 11, v[142:143]
	v_ashrrev_i32_e32 v159, 31, v158
	v_and_b32_e32 v65, -8, v158
	v_add_u32_e32 v88, 0xfc, v87
	v_writelane_b32 v250, s6, 51
	v_add_u32_e32 v77, 49, v158
	v_add_u32_e32 v79, 50, v158
	v_add_u32_e32 v80, 51, v158
	v_or_b32_e32 v66, s84, v66
	v_lshl_add_u32 v70, v70, 2, s8
	v_mul_lo_u32 v76, v75, s9
	v_add_u32_e32 v83, s8, v196
	v_lshl_add_u32 v84, v75, 1, s8
	v_add_u32_e32 v64, v65, v64
	v_and_b32_e32 v202, 0xfc, v88
	v_add_u32_e32 v88, 0xf8, v87
	v_writelane_b32 v250, s7, 52
	v_cmp_gt_i32_e64 s[44:45], v80, v75
	v_cmp_gt_i32_e64 s[6:7], v79, v75
	v_cmp_gt_i32_e64 s[8:9], v77, v75
	v_add_u32_e32 v77, 0x41, v158
	v_add_u32_e32 v79, 0x42, v158
	v_add_u32_e32 v80, 0x43, v158
	v_lshl_add_u64 v[182:183], v[72:73], 0, s[92:93]
	v_lshl_add_u64 v[72:73], v[158:159], 1, v[66:67]
	s_mov_b64 s[84:85], 0x526e040
	v_ashrrev_i32_e32 v65, 31, v64
	v_and_b32_e32 v203, 0xfc, v88
	v_add_u32_e32 v88, 0xf0, v87
	v_cmp_gt_i32_e64 s[52:53], v80, v75
	v_cmp_gt_i32_e64 s[54:55], v79, v75
	v_cmp_gt_i32_e64 s[56:57], v77, v75
	v_add_u32_e32 v77, 0x51, v158
	v_add_u32_e32 v79, 0x52, v158
	v_add_u32_e32 v80, 0x53, v158
	v_lshl_add_u64 v[186:187], v[72:73], 0, s[84:85]
	v_readlane_b32 s84, v250, 12
	v_and_b32_e32 v204, 0xfc, v88
	v_add_u32_e32 v88, 0xe0, v87
	v_cmp_gt_i32_e64 s[60:61], v80, v75
	v_cmp_gt_i32_e64 s[62:63], v79, v75
	v_cmp_gt_i32_e64 s[64:65], v77, v75
	v_add_u32_e32 v77, 0x61, v158
	v_add_u32_e32 v79, 0x62, v158
	v_add_u32_e32 v80, 0x63, v158
	v_lshl_add_u64 v[64:65], v[64:65], 1, v[66:67]
	v_readlane_b32 s85, v250, 13
	v_add_u32_e32 v195, 16, v76
	v_add_u32_e32 v78, 16, v196
	v_add_u32_e32 v76, s19, v76
	v_mul_u32_u24_e32 v86, 0x110, v192
	v_and_b32_e32 v205, 0xfc, v88
	v_add_u32_e32 v88, 0xc0, v87
	s_mov_b64 s[20:21], 0x1800
	v_cmp_gt_i32_e64 s[68:69], v80, v75
	v_cmp_gt_i32_e64 s[70:71], v79, v75
	v_cmp_gt_i32_e64 s[72:73], v77, v75
	v_add_u32_e32 v77, 0x71, v158
	v_add_u32_e32 v79, 0x72, v158
	v_add_u32_e32 v80, 0x73, v158
	v_lshl_add_u64 v[188:189], s[84:85], 0, v[64:65]
	v_mov_b32_e32 v64, 0
	s_mov_b32 s40, 0
	v_add_u32_e32 v199, s18, v196
	v_and_b32_e32 v206, 0xfc, v88
	v_lshl_add_u64 v[162:163], v[150:151], 0, s[20:21]
	v_add_u32_e32 v169, 0xffffff00, v168
	v_lshl_add_u64 v[170:171], v[156:157], 0, s[20:21]
	v_cmp_gt_i32_e64 s[18:19], v158, v75
	v_cmp_lt_i32_e64 s[20:21], v158, v75
	v_mov_b32_e32 v145, v144
	v_cmp_gt_i32_e64 s[76:77], v80, v75
	v_cmp_gt_i32_e64 s[78:79], v79, v75
	v_cmp_gt_i32_e64 s[80:81], v77, v75
	v_add_u32_e32 v219, v69, v86
	v_add_u32_e32 v220, v70, v71
	v_add_u32_e32 v221, v76, v196
	v_add_u32_e32 v222, v85, v86
	v_add_u32_e32 v223, v78, v86
	v_add_u32_e32 v224, v82, v86
	v_add_u32_e32 v225, v83, v86
	v_add_u32_e32 v226, v84, v74
	v_mov_b32_e32 v65, v64
	v_mov_b32_e32 v66, v64
	v_mov_b32_e32 v67, v64
	v_mov_b32_e32 v76, v64
	v_mov_b32_e32 v77, v64
	v_mov_b32_e32 v78, v64
	v_mov_b32_e32 v79, v64
	v_mov_b32_e32 v72, v64
	v_mov_b32_e32 v73, v64
	v_mov_b32_e32 v74, v64
	v_mov_b32_e32 v75, v64
	v_mov_b32_e32 v68, v64
	v_mov_b32_e32 v69, v64
	v_mov_b32_e32 v70, v64
	v_mov_b32_e32 v71, v64
	global_load_dwordx4 v[32:35], v[154:155], off offset:16
	global_load_dwordx4 v[36:39], v[154:155], off
	global_load_dwordx4 v[244:247], v[156:157], off offset:16
	s_waitcnt vmcnt(0)
	ds_write_b128 v43, v[32:35] offset:0
	ds_write_b128 v43, v[36:39] offset:16
	ds_write_b128 v43, v[244:247] offset:32
	global_load_dwordx4 v[32:35], v[156:157], off
	global_load_dwordx4 v[36:39], v[170:171], off offset:16
	global_load_dwordx4 v[244:247], v[170:171], off
	s_waitcnt vmcnt(0)
	ds_write_b128 v43, v[32:35] offset:48
	ds_write_b128 v43, v[36:39] offset:64
	ds_write_b128 v43, v[244:247] offset:80
	global_load_dwordx4 v[32:35], v[172:173], off offset:16
	global_load_dwordx4 v[36:39], v[172:173], off
	global_load_dwordx4 v[244:247], v[174:175], off offset:16
	s_waitcnt vmcnt(0)
	ds_write_b128 v43, v[32:35] offset:96
	ds_write_b128 v43, v[36:39] offset:112
	ds_write_b128 v43, v[244:247] offset:128
	global_load_dwordx4 v[32:35], v[174:175], off
	s_waitcnt vmcnt(0)
	ds_write_b128 v43, v[32:35] offset:144
	s_waitcnt lgkmcnt(0)
	s_branch .LBB0_570

; __device__ __forceinline__ float bflo(unsigned w) { return __uint_as_float(w << 16); }
; __device__ __forceinline__ float bfhi(unsigned w) { return __uint_as_float(w & 0xffff0000u); }
; __device__ __forceinline__ float silu_f(float x) { return x * __builtin_amdgcn_rcpf(1.f + __builtin_amdgcn_exp2f(-1.4426950409f * x)); }
; __device__ __forceinline__ void ssd_prompt_item(const Params& p, int item, const int wv) {
;     ...
;       f32x4 b0 = *(const f32x4*)(convb + colx), b1 = *(const f32x4*)(convb + colx + 4);
;       f32x4 w0[4], w1[4];
; #pragma unroll
;       for (int k = 0; k < 4; ++k) { w0[k] = *(const f32x4*)(convw + k * 1536 + colx); w1[k] = *(const f32x4*)(convw + k * 1536 + colx + 4); }
;       float xo[2][8];
; #pragma unroll
;       for (int r2 = 0; r2 < 2; ++r2) {
;         float o[8] = {b0[0], b0[1], b0[2], b0[3], b1[0], b1[1], b1[2], b1[3]};
; #pragma unroll
;         for (int k = 0; k < 4; ++k) {
;           u32x4 uu = ux[r2 + k];
;           o[0] += w0[k][0] * bflo(uu.x); o[1] += w0[k][1] * bfhi(uu.x); o[2] += w0[k][2] * bflo(uu.y); o[3] += w0[k][3] * bfhi(uu.y);
;           o[4] += w1[k][0] * bflo(uu.z); o[5] += w1[k][1] * bfhi(uu.z); o[6] += w1[k][2] * bflo(uu.w); o[7] += w1[k][3] * bfhi(uu.w);
;         }
; #pragma unroll
;         for (int e = 0; e < 8; ++e) xo[r2][e] = silu_f(o[e]);
.LBB0_576:
	s_or_b64 exec, exec, s[84:85]
	ds_read_b128 v[80:83], v43 offset:0
	ds_read_b128 v[100:103], v43 offset:16
	ds_read_b128 v[84:87], v43 offset:32
	ds_read_b128 v[104:107], v43 offset:48
	ds_read_b128 v[88:91], v43 offset:64
	ds_read_b128 v[108:111], v43 offset:80
	ds_read_b128 v[92:95], v43 offset:96
	ds_read_b128 v[112:115], v43 offset:112
	ds_read_b128 v[96:99], v43 offset:128
	ds_read_b128 v[116:119], v43 offset:144
	v_lshlrev_b32_e32 v120, 16, v44
	v_lshlrev_b32_e32 v121, 16, v48
	v_lshlrev_b32_e32 v123, 16, v52
	v_mov_b32_e32 v122, v121
	v_lshlrev_b32_e32 v127, 16, v56
	v_mov_b32_e32 v126, v123
	v_lshlrev_b32_e32 v125, 16, v60
	v_mov_b32_e32 v124, v127
	v_and_b32_e32 v129, 0xffff0000, v60
	s_cmpk_eq_i32 s40, 0x780
	s_waitcnt lgkmcnt(6)
	v_pk_fma_f32 v[120:121], v[104:105], v[120:121], v[100:101] op_sel_hi:[0,1,0]
	s_waitcnt lgkmcnt(4)
	v_pk_fma_f32 v[120:121], v[108:109], v[122:123], v[120:121] op_sel_hi:[0,1,1]
	s_waitcnt lgkmcnt(2)
	v_pk_fma_f32 v[120:121], v[112:113], v[126:127], v[120:121] op_sel_hi:[0,1,1]
	v_and_b32_e32 v127, 0xffff0000, v56
	s_waitcnt lgkmcnt(0)
	v_pk_fma_f32 v[120:121], v[116:117], v[124:125], v[120:121] op_sel_hi:[0,1,1]
	v_mul_f32_e32 v122, 0xbfb8aa3b, v120
	v_mul_f32_e32 v123, 0xbfb8aa3b, v121
	v_exp_f32_e32 v122, v122
	v_exp_f32_e32 v123, v123
	v_and_b32_e32 v125, 0xffff0000, v52
	v_mov_b32_e32 v126, v125
	v_add_f32_e32 v122, 1.0, v122
	v_add_f32_e32 v123, 1.0, v123
	v_rcp_f32_e32 v122, v122
	v_rcp_f32_e32 v123, v123
	v_mov_b32_e32 v128, v127
	v_pk_mul_f32 v[120:121], v[120:121], v[122:123]
	v_and_b32_e32 v123, 0xffff0000, v48
	v_and_b32_e32 v122, 0xffff0000, v44
	v_mov_b32_e32 v124, v123
	v_pk_fma_f32 v[100:101], v[104:105], v[122:123], v[100:101] op_sel:[1,0,1]
	v_and_b32_e32 v123, 0xffff0000, v61
	v_pk_fma_f32 v[100:101], v[108:109], v[124:125], v[100:101] op_sel:[1,0,0]
	v_lshlrev_b32_e32 v109, 16, v53
	v_pk_fma_f32 v[100:101], v[112:113], v[126:127], v[100:101] op_sel:[1,0,0]
	v_lshlrev_b32_e32 v113, 16, v61
	v_pk_fma_f32 v[100:101], v[116:117], v[128:129], v[100:101] op_sel:[1,0,0]
	v_lshlrev_b32_e32 v117, 16, v57
	v_mul_f32_e32 v104, 0xbfb8aa3b, v100
	v_mul_f32_e32 v105, 0xbfb8aa3b, v101
	v_exp_f32_e32 v104, v104
	v_exp_f32_e32 v105, v105
	v_mov_b32_e32 v116, v109
	v_mov_b32_e32 v112, v117
	v_add_f32_e32 v104, 1.0, v104
	v_add_f32_e32 v105, 1.0, v105
	v_rcp_f32_e32 v104, v104
	v_rcp_f32_e32 v105, v105
	s_nop 0
	v_pk_mul_f32 v[100:101], v[100:101], v[104:105]
	v_lshlrev_b32_e32 v104, 16, v45
	v_lshlrev_b32_e32 v105, 16, v49
	v_mov_b32_e32 v108, v105
	v_pk_fma_f32 v[104:105], v[106:107], v[104:105], v[102:103] op_sel_hi:[0,1,0]
	v_pk_fma_f32 v[104:105], v[110:111], v[108:109], v[104:105] op_sel_hi:[0,1,1]
	v_pk_fma_f32 v[104:105], v[114:115], v[116:117], v[104:105] op_sel_hi:[0,1,1]
	v_pk_fma_f32 v[104:105], v[118:119], v[112:113], v[104:105] op_sel_hi:[0,1,1]
	v_mul_f32_e32 v102, 0xbfb8aa3b, v104
	v_exp_f32_e32 v102, v102
	v_mov_b32_e32 v106, v103
	v_and_b32_e32 v113, 0xffff0000, v53
	v_and_b32_e32 v117, 0xffff0000, v57
	v_add_f32_e32 v102, 1.0, v102
	v_rcp_f32_e32 v108, v102
	v_mul_f32_e32 v102, 0xbfb8aa3b, v105
	v_exp_f32_e32 v102, v102
	v_mov_b32_e32 v116, v113
	v_mov_b32_e32 v122, v117
	v_add_f32_e32 v102, 1.0, v102
	v_rcp_f32_e32 v109, v102
	v_mov_b32_e32 v102, v107
	v_pk_mul_f32 v[104:105], v[104:105], v[108:109]
	v_and_b32_e32 v109, 0xffff0000, v49
	v_and_b32_e32 v108, 0xffff0000, v45
	v_mov_b32_e32 v112, v109
	v_pk_fma_f32 v[102:103], v[102:103], v[108:109], v[106:107] op_sel_hi:[0,1,0]
	v_mov_b32_e32 v106, v111
	v_pk_fma_f32 v[102:103], v[106:107], v[112:113], v[102:103] op_sel_hi:[0,1,1]
	v_mov_b32_e32 v106, v115
	v_pk_fma_f32 v[102:103], v[106:107], v[116:117], v[102:103] op_sel_hi:[0,1,1]
	v_mov_b32_e32 v106, v119
	v_pk_fma_f32 v[102:103], v[106:107], v[122:123], v[102:103] op_sel_hi:[0,1,1]
	v_mul_f32_e32 v106, 0xbfb8aa3b, v102
	v_mul_f32_e32 v107, 0xbfb8aa3b, v103
	v_exp_f32_e32 v106, v106
	v_exp_f32_e32 v107, v107
	v_lshlrev_b32_e32 v109, 16, v54
	v_lshlrev_b32_e32 v113, 16, v58
	v_add_f32_e32 v106, 1.0, v106
	v_add_f32_e32 v107, 1.0, v107
	v_rcp_f32_e32 v106, v106
	v_rcp_f32_e32 v107, v107
	v_mov_b32_e32 v112, v109
	v_lshlrev_b32_e32 v111, 16, v62
	v_mov_b32_e32 v110, v113
	v_pk_mul_f32 v[102:103], v[102:103], v[106:107]
	v_lshlrev_b32_e32 v106, 16, v46
	v_lshlrev_b32_e32 v107, 16, v50
	v_mov_b32_e32 v108, v107
	v_pk_fma_f32 v[106:107], v[84:85], v[106:107], v[80:81] op_sel_hi:[0,1,0]
	v_pk_fma_f32 v[106:107], v[88:89], v[108:109], v[106:107] op_sel_hi:[0,1,1]
	v_pk_fma_f32 v[106:107], v[92:93], v[112:113], v[106:107] op_sel_hi:[0,1,1]
	v_pk_fma_f32 v[106:107], v[96:97], v[110:111], v[106:107] op_sel_hi:[0,1,1]
	v_mul_f32_e32 v108, 0xbfb8aa3b, v106
	v_mul_f32_e32 v109, 0xbfb8aa3b, v107
	v_exp_f32_e32 v108, v108
	v_exp_f32_e32 v109, v109
	v_and_b32_e32 v111, 0xffff0000, v54
	v_and_b32_e32 v113, 0xffff0000, v58
	v_add_f32_e32 v108, 1.0, v108
	v_add_f32_e32 v109, 1.0, v109
	v_rcp_f32_e32 v108, v108
	v_rcp_f32_e32 v109, v109
; __device__ __forceinline__ unsigned cvt_pk(float lo, float hi) { f32x2 v = {lo, hi}; bf16x2_t b = __builtin_convertvector(v, bf16x2_t); return __builtin_bit_cast(unsigned, b); }
; __device__ __forceinline__ float bflo(unsigned w) { return __uint_as_float(w << 16); }
; __device__ __forceinline__ float bfhi(unsigned w) { return __uint_as_float(w & 0xffff0000u); }
; __device__ __forceinline__ float silu_f(float x) { return x * __builtin_amdgcn_rcpf(1.f + __builtin_amdgcn_exp2f(-1.4426950409f * x)); }
; __device__ __forceinline__ void ssd_prompt_item(const Params& p, int item, const int wv) {
;     ...
;       float xo[2][8];
; #pragma unroll
;       for (int r2 = 0; r2 < 2; ++r2) {
;         float o[8] = {b0[0], b0[1], b0[2], b0[3], b1[0], b1[1], b1[2], b1[3]};
; #pragma unroll
;         for (int k = 0; k < 4; ++k) {
;           u32x4 uu = ux[r2 + k];
;           o[0] += w0[k][0] * bflo(uu.x); o[1] += w0[k][1] * bfhi(uu.x); o[2] += w0[k][2] * bflo(uu.y); o[3] += w0[k][3] * bfhi(uu.y);
;           o[4] += w1[k][0] * bflo(uu.z); o[5] += w1[k][1] * bfhi(uu.z); o[6] += w1[k][2] * bflo(uu.w); o[7] += w1[k][3] * bfhi(uu.w);
;         }
; #pragma unroll
;         for (int e = 0; e < 8; ++e) xo[r2][e] = silu_f(o[e]);
;       }
; #pragma unroll
;       for (int e = 0; e < 8; ++e) *(unsigned*)(xT_l + (xc * 8 + e) * 136 + 2 * xr) = cvt_pk(xo[0][e], xo[1][e]);
;     }
;     __syncthreads();
;     if (c < 15) SSD_PREFETCH(c + 1);
	v_mov_b32_e32 v112, v111
	v_and_b32_e32 v115, 0xffff0000, v62
	v_mov_b32_e32 v114, v113
	v_pk_mul_f32 v[106:107], v[106:107], v[108:109]
	v_and_b32_e32 v109, 0xffff0000, v50
	v_and_b32_e32 v108, 0xffff0000, v46
	v_mov_b32_e32 v110, v109
	v_pk_fma_f32 v[80:81], v[84:85], v[108:109], v[80:81] op_sel:[1,0,1]
	v_and_b32_e32 v109, 0xffff0000, v63
	v_pk_fma_f32 v[80:81], v[88:89], v[110:111], v[80:81] op_sel:[1,0,0]
	v_lshlrev_b32_e32 v89, 16, v55
	v_pk_fma_f32 v[80:81], v[92:93], v[112:113], v[80:81] op_sel:[1,0,0]
	v_lshlrev_b32_e32 v93, 16, v63
	v_pk_fma_f32 v[80:81], v[96:97], v[114:115], v[80:81] op_sel:[1,0,0]
	v_lshlrev_b32_e32 v97, 16, v59
	v_mul_f32_e32 v84, 0xbfb8aa3b, v80
	v_mul_f32_e32 v85, 0xbfb8aa3b, v81
	v_exp_f32_e32 v84, v84
	v_exp_f32_e32 v85, v85
	v_mov_b32_e32 v96, v89
	v_mov_b32_e32 v92, v97
	v_add_f32_e32 v84, 1.0, v84
	v_add_f32_e32 v85, 1.0, v85
	v_rcp_f32_e32 v84, v84
	v_rcp_f32_e32 v85, v85
	s_nop 0
	v_pk_mul_f32 v[80:81], v[80:81], v[84:85]
	v_lshlrev_b32_e32 v84, 16, v47
	v_lshlrev_b32_e32 v85, 16, v51
	v_mov_b32_e32 v88, v85
	v_pk_fma_f32 v[84:85], v[86:87], v[84:85], v[82:83] op_sel_hi:[0,1,0]
	v_pk_fma_f32 v[84:85], v[90:91], v[88:89], v[84:85] op_sel_hi:[0,1,1]
	v_pk_fma_f32 v[84:85], v[94:95], v[96:97], v[84:85] op_sel_hi:[0,1,1]
	v_pk_fma_f32 v[84:85], v[98:99], v[92:93], v[84:85] op_sel_hi:[0,1,1]
	v_mul_f32_e32 v82, 0xbfb8aa3b, v84
	v_exp_f32_e32 v82, v82
	v_mov_b32_e32 v86, v83
	v_and_b32_e32 v93, 0xffff0000, v55
	v_and_b32_e32 v97, 0xffff0000, v59
	v_add_f32_e32 v82, 1.0, v82
	v_rcp_f32_e32 v88, v82
	v_mul_f32_e32 v82, 0xbfb8aa3b, v85
	v_exp_f32_e32 v82, v82
	v_mov_b32_e32 v96, v93
	v_mov_b32_e32 v108, v97
	v_cvt_pk_bf16_f32 v80, v80, v81
	v_add_f32_e32 v82, 1.0, v82
	v_rcp_f32_e32 v89, v82
	v_mov_b32_e32 v82, v87
	v_add_u32_e32 v81, 0x400, v220
	v_pk_mul_f32 v[84:85], v[84:85], v[88:89]
	v_and_b32_e32 v89, 0xffff0000, v51
	v_and_b32_e32 v88, 0xffff0000, v47
	v_mov_b32_e32 v92, v89
	v_pk_fma_f32 v[82:83], v[82:83], v[88:89], v[86:87] op_sel_hi:[0,1,0]
	v_mov_b32_e32 v86, v91
	v_pk_fma_f32 v[82:83], v[86:87], v[92:93], v[82:83] op_sel_hi:[0,1,1]
	v_mov_b32_e32 v86, v95
	v_pk_fma_f32 v[82:83], v[86:87], v[96:97], v[82:83] op_sel_hi:[0,1,1]
	v_mov_b32_e32 v86, v99
	v_pk_fma_f32 v[82:83], v[86:87], v[108:109], v[82:83] op_sel_hi:[0,1,1]
	v_mul_f32_e32 v86, 0xbfb8aa3b, v82
	v_mul_f32_e32 v87, 0xbfb8aa3b, v83
	v_exp_f32_e32 v86, v86
	v_exp_f32_e32 v87, v87
	v_add_f32_e32 v86, 1.0, v86
	v_add_f32_e32 v87, 1.0, v87
	v_rcp_f32_e32 v86, v86
	v_rcp_f32_e32 v87, v87
	s_nop 0
	v_pk_mul_f32 v[82:83], v[82:83], v[86:87]
	v_cvt_pk_bf16_f32 v86, v120, v121
	v_cvt_pk_bf16_f32 v87, v100, v101
	ds_write2_b32 v220, v86, v87 offset1:68
	v_cvt_pk_bf16_f32 v86, v104, v105
	v_cvt_pk_bf16_f32 v87, v102, v103
	ds_write2_b32 v220, v86, v87 offset0:136 offset1:204
	v_cvt_pk_bf16_f32 v86, v106, v107
	ds_write2_b32 v81, v86, v80 offset0:16 offset1:84
	v_cvt_pk_bf16_f32 v80, v84, v85
	v_cvt_pk_bf16_f32 v82, v82, v83
	ds_write2_b32 v81, v80, v82 offset0:152 offset1:220
	s_waitcnt lgkmcnt(0)
	s_barrier
	s_cbranch_scc1 .LBB0_579
	v_add_u32_e32 v40, s40, v218
	v_lshl_add_u64 v[48:49], s[50:51], 0, v[180:181]
	v_add_co_u32_e32 v52, vcc, 0x72ae000, v48
	v_lshl_add_u64 v[44:45], s[50:51], 0, v[182:183]
	v_addc_co_u32_e32 v53, vcc, 0, v49, vcc
	v_lshl_add_u64 v[56:57], s[50:51], 0, v[176:177]
	v_lshl_add_u64 v[60:61], s[50:51], 0, v[178:179]
	s_nop 0
	s_nop 0
	s_nop 0
	s_nop 0
	s_nop 0
	s_nop 0
	s_nop 0
	s_nop 0
	s_nop 0
	s_nop 0
	s_nop 0
	s_add_u32 s84, s40, 0x80
	s_lshl_b32 s84, s84, 10
	v_mov_b32_e32 v248, s84
	s_nop 0
	v_lshl_add_u64 v[244:245], v[248:249], 0, v[242:243]
	v_mov_b32_e32 v248, 0x1000
	s_nop 0
	v_lshl_add_u64 v[246:247], v[248:249], 0, v[244:245]
	global_load_dwordx4 v[0:3], v[244:245], off
	global_load_dwordx4 v[4:7], v[244:245], off offset:1024
	global_load_dwordx4 v[8:11], v[244:245], off offset:2048
	global_load_dwordx4 v[12:15], v[244:245], off offset:3072
	global_load_dwordx4 v[16:19], v[246:247], off
	global_load_dwordx4 v[20:23], v[246:247], off offset:1024
	global_load_dwordx4 v[24:27], v[246:247], off offset:2048
	global_load_dwordx4 v[28:31], v[246:247], off offset:3072
	global_load_dwordx4 v[44:47], v[44:45], off
	s_nop 0
	global_load_dwordx4 v[48:51], v[52:53], off
	s_nop 0
	global_load_dwordx4 v[52:55], v[52:53], off offset:3072
	s_nop 0
	global_load_dwordx4 v[56:59], v[56:57], off
	s_nop 0
	global_load_dwordx4 v[60:63], v[60:61], off
	v_readlane_b32 s84, v251, 58
	v_readlane_b32 s85, v251, 59
	s_and_b64 vcc, exec, s[84:85]
	s_cbranch_vccnz .LBB0_579
	v_add_u32_e32 v82, s40, v217
	v_add_u32_e32 v80, 0x80, v82
	v_ashrrev_i32_e32 v81, 31, v80
	v_lshlrev_b64 v[80:81], 6, v[80:81]
	v_lshl_add_u64 v[80:81], s[12:13], 0, v[80:81]
	global_load_dword v148, v[80:81], off
	v_add_u32_e32 v80, 0x81, v82
	v_ashrrev_i32_e32 v81, 31, v80
	v_lshlrev_b64 v[80:81], 6, v[80:81]
	v_lshl_add_u64 v[80:81], s[12:13], 0, v[80:81]
	global_load_dword v149, v[80:81], off
